# cache policy: norm phase's residual-row loads non-temporal
# speedup vs baseline: 1.0068x; 1.0068x over previous
; __device__ __forceinline__ void norm_phase(const float* xs_lat, const float* xs_ctx, const float* partA, const float* partB, float* xc_wr, int row_begin, int rows, const float* gain, const float* modl, int shoff, int scoff, bf16_t* H, int gw, int NGW, int lane) {
;     ...
;         for (int u = 0; u < 2; ++u) { const int row = row0 + u * NGW; ok[u] = row < rows; const bool lat = row < ML; latv[u] = lat;
;             if (ok[u]) { const f32x4* xr = (const f32x4*)(lat ? xs_lat + (size_t)row * D : xs_ctx + (size_t)(row - ML) * D) + lane;
; #pragma unroll
;                 for (int j = 0; j < 4; ++j) v[u][j] = xr[64 * j]; } }
.LBB0_1160:
	s_add_i32 s34, s3, 0xffffc000
	s_add_u32 s22, s6, s8
	s_addc_u32 s23, s7, s9
	s_cmpk_lt_i32 s3, 0x4000
	s_cselect_b64 s[42:43], -1, 0
	s_and_b64 s[4:5], s[42:43], exec
	s_cselect_b32 s5, s23, 0
	s_cselect_b32 s4, s22, s34
	s_cselect_b32 s22, s45, s67
	s_cselect_b32 s23, s44, s66
	s_lshl_b64 s[4:5], s[4:5], 12
	s_add_u32 s4, s23, s4
	s_addc_u32 s5, s22, s5
	v_lshlrev_b32_e32 v52, 4, v32
	global_load_dwordx4 v[20:23], v52, s[4:5] nt
	global_load_dwordx4 v[28:31], v52, s[4:5] offset:1024 nt
	global_load_dwordx4 v[16:19], v52, s[4:5] offset:2048 nt
	global_load_dwordx4 v[24:27], v52, s[4:5] offset:3072 nt
	s_add_i32 s24, s26, s3
	s_cmp_lt_i32 s24, s38
	s_cselect_b64 s[40:41], -1, 0
	s_cmpk_lt_i32 s24, 0x4000
	s_cselect_b64 s[30:31], -1, 0
	s_cmp_ge_i32 s24, s38
	s_cbranch_scc1 .LBB0_1162
	s_and_b64 s[4:5], s[30:31], exec
	s_cselect_b32 s22, s45, s67
	s_cselect_b32 s23, s44, s66
	s_add_u32 s25, s12, s8
	s_addc_u32 s27, s13, s9
	s_add_i32 s29, s24, 0xffffc000
	s_and_b64 s[4:5], s[30:31], exec
	s_cselect_b32 s5, s27, 0
	s_cselect_b32 s4, s25, s29
	s_lshl_b64 s[4:5], s[4:5], 12
	s_add_u32 s4, s23, s4
	s_addc_u32 s5, s22, s5
	global_load_dwordx4 v[4:7], v52, s[4:5] nt
	global_load_dwordx4 v[8:11], v52, s[4:5] offset:1024 nt
	global_load_dwordx4 v[0:3], v52, s[4:5] offset:2048 nt
	global_load_dwordx4 v[12:15], v52, s[4:5] offset:3072 nt
